# speedup vs baseline: 1.0045x; 1.0045x over previous
; __device__ __forceinline__ void attn_exp(f32x16& sa, float mx, float& m_run, float& lsum, f32x16 (&o)[4], bf16x8& pb0, bf16x8& pb1) {
;     ...
;     float pv[16];
; #pragma unroll
;     for (int r = 0; r < 16; ++r) { pv[r] = __builtin_amdgcn_exp2f(sa[r] - m_run); lsum += pv[r]; }
;     u32x4 t0 = {pack2(pv[0], pv[1]), pack2(pv[2], pv[3]), pack2(pv[4], pv[5]), pack2(pv[6], pv[7])};
;     u32x4 t1 = {pack2(pv[8], pv[9]), pack2(pv[10], pv[11]), pack2(pv[12], pv[13]), pack2(pv[14], pv[15])};
;     pb0 = __builtin_bit_cast(bf16x8, t0);
;     pb1 = __builtin_bit_cast(bf16x8, t1);
; template <bool MLA>
; __device__ __forceinline__ void attn_item(unsigned char* smem, const Params& p, int b, int hh, int qt) {
;     ...
;                 for (int i = 0; i < 4; ++i) {
;                     sa = __builtin_amdgcn_mfma_f32_32x32x16_bf16(ka[i], qf[i], sa, 0, 0, 0);
;                     kb[i] = KRD(hf, 4 + i);
;                 }
;                 SB_();
; #pragma unroll
;                 for (int i = 0; i < 4; ++i) {
;                     sa = __builtin_amdgcn_mfma_f32_32x32x16_bf16(kb[i], qf[4 + i], sa, 0, 0, 0);
;                     kc[i] = KRD(hf, 8 + i);
;                 }
;                 SB_();
; #pragma unroll
;                 for (int d = 0; d < 2; ++d) { vf[2 * d] = VRD(hf, d, 0); vf[2 * d + 1] = VRD(hf, d, 1); }
; #pragma unroll
;                 for (int i = 0; i < 4; ++i) sa = __builtin_amdgcn_mfma_f32_32x32x16_bf16(kc[i], qf[8 + i], sa, 0, 0, 0);
;                 __builtin_amdgcn_s_setprio(0);
;             } else {
; #pragma unroll
;                 for (int i = 0; i < 4; ++i) sa = __builtin_amdgcn_mfma_f32_32x32x16_bf16(ka[i], qf[i], sa, 0, 0, 0);
;                 SB_();
;                 const float mx = attn_scores<false>(sa, c1, slope2, qpos, q0w, k0 + hf * 32, h5, kt == NKT - 1);
;                 const bool skip = __all(mx < m_run - 40.0f);
;                 if (hf == 0 && kt != NKT - 1) {
; #pragma unroll
;                     for (int i = 0; i < 4; ++i) ka[i] = KRD(1, i);
;                 }
;                 if (!skip) {
; #pragma unroll
;                     for (int d = 0; d < 4; ++d) { vf[2 * d] = VRD(hf, d, 0); vf[2 * d + 1] = VRD(hf, d, 1); }
;                     bf16x8 pb0, pb1;
;                     attn_exp(sa, mx, m_run, lsum, o, pb0, pb1);
;                     SB_();
; #pragma unroll
;                     for (int d = 0; d < 4; ++d) {
.LBB0_869:
	v_sub_f32_e32 v74, v217, v198
	v_exp_f32_e32 v222, v74
	v_sub_f32_e32 v74, v216, v198
	v_exp_f32_e32 v223, v74
	v_sub_f32_e32 v74, v215, v198
	v_exp_f32_e32 v224, v74
	v_sub_f32_e32 v74, v214, v198
	v_exp_f32_e32 v225, v74
	v_sub_f32_e32 v74, v213, v198
	v_exp_f32_e32 v226, v74
	v_sub_f32_e32 v74, v212, v198
	v_exp_f32_e32 v227, v74
	v_sub_f32_e32 v74, v211, v198
	v_exp_f32_e32 v228, v74
	v_sub_f32_e32 v74, v210, v198
	v_sub_f32_e32 v73, v73, v198
	v_sub_f32_e32 v72, v72, v198
	v_sub_f32_e32 v71, v71, v198
	v_sub_f32_e32 v70, v70, v198
	v_sub_f32_e32 v69, v69, v198
	v_sub_f32_e32 v68, v68, v198
	v_sub_f32_e32 v67, v67, v198
	v_sub_f32_e32 v66, v66, v198
	v_exp_f32_e32 v229, v74
	v_exp_f32_e32 v230, v73
	v_exp_f32_e32 v231, v72
	v_exp_f32_e32 v232, v71
	v_exp_f32_e32 v233, v70
	v_exp_f32_e32 v234, v69
	v_exp_f32_e32 v235, v68
	v_exp_f32_e32 v236, v67
	v_exp_f32_e32 v237, v66
	v_cvt_pk_bf16_f32 v66, v222, v223
	v_cvt_pk_bf16_f32 v67, v224, v225
	v_cvt_pk_bf16_f32 v68, v226, v227
	v_cvt_pk_bf16_f32 v69, v228, v229
	v_cvt_pk_bf16_f32 v70, v230, v231
	v_cvt_pk_bf16_f32 v71, v232, v233
	v_cvt_pk_bf16_f32 v72, v234, v235
	v_cvt_pk_bf16_f32 v73, v236, v237
	v_add_f32_e32 v201, v201, v222
	v_add_f32_e32 v201, v223, v201
	v_add_f32_e32 v201, v224, v201
	v_add_f32_e32 v201, v225, v201
	v_add_f32_e32 v201, v226, v201
	v_add_f32_e32 v201, v227, v201
	v_add_f32_e32 v201, v228, v201
	v_add_f32_e32 v201, v229, v201
	v_add_f32_e32 v201, v230, v201
	v_add_f32_e32 v201, v231, v201
	v_add_f32_e32 v201, v232, v201
	v_add_f32_e32 v201, v233, v201
	v_add_f32_e32 v201, v234, v201
	v_add_f32_e32 v201, v235, v201
	v_add_f32_e32 v201, v236, v201
	ds_read_b128 v[74:77], v208 offset:32768
	ds_read_b128 v[78:81], v207 offset:32768
	ds_read_b128 v[210:213], v208 offset:36864
	ds_read_b128 v[214:217], v207 offset:36864
	v_add_f32_e32 v201, v237, v201
	ds_read_b128 v[222:225], v203 offset:12288
	ds_read_b128 v[226:229], v204 offset:12288
	ds_read_b128 v[230:233], v205 offset:12288
	ds_read_b128 v[234:237], v206 offset:12288
	s_setprio 1
	v_mfma_f32_32x32x16_bf16 v[50:65], v[138:141], v[66:69], v[50:65]
	v_mfma_f32_32x32x16_bf16 v[34:49], v[130:133], v[66:69], v[34:49]
	s_waitcnt lgkmcnt(4)
	v_mfma_f32_32x32x16_bf16 v[18:33], v[74:77], v[66:69], v[18:33]
	v_mfma_f32_32x32x16_bf16 v[2:17], v[210:213], v[66:69], v[2:17]
	v_mfma_f32_32x32x16_bf16 v[50:65], v[142:145], v[70:73], v[50:65]
	v_mfma_f32_32x32x16_bf16 v[34:49], v[134:137], v[70:73], v[34:49]
	v_mfma_f32_32x32x16_bf16 v[18:33], v[78:81], v[70:73], v[18:33]
	v_mfma_f32_32x32x16_bf16 v[2:17], v[214:217], v[70:73], v[2:17]
	s_setprio 0
	s_setprio 1
	s_waitcnt lgkmcnt(0)
	v_mfma_f32_32x32x16_bf16 v[66:81], v[222:225], v[110:113], 0
	ds_read_b128 v[130:133], v203 offset:12416
	ds_read_b128 v[134:137], v204 offset:12416
	ds_read_b128 v[138:141], v205 offset:12416
	ds_read_b128 v[142:145], v206 offset:12416
	v_mfma_f32_32x32x16_bf16 v[66:81], v[226:229], v[106:109], v[66:81]
	v_mfma_f32_32x32x16_bf16 v[66:81], v[230:233], v[102:105], v[66:81]
	v_mfma_f32_32x32x16_bf16 v[66:81], v[234:237], v[98:101], v[66:81]
	ds_read_b128 v[210:213], v203 offset:12544
	ds_read_b128 v[214:217], v204 offset:12544
	ds_read_b128 v[222:225], v205 offset:12544
	ds_read_b128 v[204:207], v206 offset:12544
	s_waitcnt lgkmcnt(0)
	v_mfma_f32_32x32x16_bf16 v[66:81], v[130:133], v[94:97], v[66:81]
	v_add_u32_e32 v203, v202, v196
	v_add_u32_e32 v202, v202, v197
	v_mfma_f32_32x32x16_bf16 v[66:81], v[134:137], v[90:93], v[66:81]
	v_mfma_f32_32x32x16_bf16 v[66:81], v[138:141], v[86:89], v[66:81]
	v_mfma_f32_32x32x16_bf16 v[66:81], v[142:145], v[82:85], v[66:81]
	ds_read_b128 v[138:141], v203 offset:24576
	ds_read_b128 v[130:133], v203 offset:28672
	ds_read_b128 v[142:145], v202 offset:24576
	ds_read_b128 v[134:137], v202 offset:28672
	v_mfma_f32_32x32x16_bf16 v[66:81], v[210:213], v[118:121], v[66:81]
	v_mfma_f32_32x32x16_bf16 v[66:81], v[214:217], v[126:129], v[66:81]
	v_mfma_f32_32x32x16_bf16 v[66:81], v[222:225], v[114:117], v[66:81]
	v_mfma_f32_32x32x16_bf16 v[66:81], v[204:207], v[122:125], v[66:81]
	s_setprio 0
	s_nop 10
	v_mul_f32_e32 v212, 0x3dd53b94, v66
	v_mul_f32_e32 v211, 0x3dd53b94, v67
	v_mul_f32_e32 v210, 0x3dd53b94, v68
	v_mul_f32_e32 v208, 0x3dd53b94, v69
	v_mul_f32_e32 v204, 0x3dd53b94, v73
	v_mul_f32_e32 v73, 0x3dd53b94, v74
	v_max3_f32 v74, v212, s3, v211
	v_mul_f32_e32 v207, 0x3dd53b94, v70
	v_mul_f32_e32 v206, 0x3dd53b94, v71
	v_max3_f32 v74, v74, v210, v208
	v_mul_f32_e32 v205, 0x3dd53b94, v72
	v_max3_f32 v74, v74, v207, v206
	v_mul_f32_e32 v72, 0x3dd53b94, v75
	v_max3_f32 v74, v74, v205, v204
	v_mul_f32_e32 v71, 0x3dd53b94, v76
	v_mul_f32_e32 v70, 0x3dd53b94, v77
	v_max3_f32 v74, v74, v73, v72
	v_mul_f32_e32 v69, 0x3dd53b94, v78
	v_mul_f32_e32 v68, 0x3dd53b94, v79
	v_max3_f32 v74, v74, v71, v70
	v_mul_f32_e32 v67, 0x3dd53b94, v80
	v_mul_f32_e32 v66, 0x3dd53b94, v81
	v_max3_f32 v74, v74, v69, v68
	v_max3_f32 v74, v74, v67, v66
	ds_bpermute_b32 v75, v149, v74
	s_waitcnt lgkmcnt(0)
	v_max_f32_e32 v75, v75, v75
	v_max_f32_e32 v74, v74, v75
	v_cmp_le_f32_e32 vcc, v74, v209
	s_cmp_eq_u64 vcc, exec
	s_cbranch_scc1 .LBB0_866
; __device__ __forceinline__ void attn_exp(f32x16& sa, float mx, float& m_run, float& lsum, f32x16 (&o)[4], bf16x8& pb0, bf16x8& pb1) {
;     if (!__all(mx <= m_run + ATT_THR)) {
;         const float m_new = fmaxf(m_run, mx);
;         const float alpha = __builtin_amdgcn_exp2f(m_run - m_new);
;         m_run = m_new;
;         lsum *= alpha;
; #pragma unroll
;         for (int d = 0; d < 4; ++d)
; #pragma unroll
;             for (int r = 0; r < 16; ++r) o[d][r] *= alpha;
;     }
	v_max_f32_e32 v74, v74, v74
	v_max_f32_e32 v75, v198, v198
	v_max_f32_e32 v75, v75, v74
	v_sub_f32_e32 v74, v198, v75
	v_exp_f32_e32 v74, v74
	v_mov_b32_e32 v198, v75
	v_mul_f32_e32 v201, v201, v74
	v_pk_mul_f32 v[64:65], v[64:65], v[74:75] op_sel_hi:[1,0]
	v_pk_mul_f32 v[62:63], v[62:63], v[74:75] op_sel_hi:[1,0]
	v_pk_mul_f32 v[60:61], v[60:61], v[74:75] op_sel_hi:[1,0]
	v_pk_mul_f32 v[58:59], v[58:59], v[74:75] op_sel_hi:[1,0]
	v_pk_mul_f32 v[56:57], v[56:57], v[74:75] op_sel_hi:[1,0]
	v_pk_mul_f32 v[54:55], v[54:55], v[74:75] op_sel_hi:[1,0]
	v_pk_mul_f32 v[52:53], v[52:53], v[74:75] op_sel_hi:[1,0]
	v_pk_mul_f32 v[50:51], v[50:51], v[74:75] op_sel_hi:[1,0]
	v_pk_mul_f32 v[48:49], v[48:49], v[74:75] op_sel_hi:[1,0]
	v_pk_mul_f32 v[46:47], v[46:47], v[74:75] op_sel_hi:[1,0]
	v_pk_mul_f32 v[44:45], v[44:45], v[74:75] op_sel_hi:[1,0]
	v_pk_mul_f32 v[42:43], v[42:43], v[74:75] op_sel_hi:[1,0]
	v_pk_mul_f32 v[40:41], v[40:41], v[74:75] op_sel_hi:[1,0]
	v_pk_mul_f32 v[38:39], v[38:39], v[74:75] op_sel_hi:[1,0]
	v_pk_mul_f32 v[36:37], v[36:37], v[74:75] op_sel_hi:[1,0]
	v_pk_mul_f32 v[34:35], v[34:35], v[74:75] op_sel_hi:[1,0]
	v_pk_mul_f32 v[32:33], v[32:33], v[74:75] op_sel_hi:[1,0]
	v_pk_mul_f32 v[30:31], v[30:31], v[74:75] op_sel_hi:[1,0]
	v_pk_mul_f32 v[28:29], v[28:29], v[74:75] op_sel_hi:[1,0]
	v_pk_mul_f32 v[26:27], v[26:27], v[74:75] op_sel_hi:[1,0]
	v_pk_mul_f32 v[24:25], v[24:25], v[74:75] op_sel_hi:[1,0]
	v_pk_mul_f32 v[22:23], v[22:23], v[74:75] op_sel_hi:[1,0]
	v_pk_mul_f32 v[20:21], v[20:21], v[74:75] op_sel_hi:[1,0]
	v_pk_mul_f32 v[18:19], v[18:19], v[74:75] op_sel_hi:[1,0]
	v_pk_mul_f32 v[16:17], v[16:17], v[74:75] op_sel_hi:[1,0]
	v_pk_mul_f32 v[14:15], v[14:15], v[74:75] op_sel_hi:[1,0]
	v_pk_mul_f32 v[12:13], v[12:13], v[74:75] op_sel_hi:[1,0]
	v_pk_mul_f32 v[10:11], v[10:11], v[74:75] op_sel_hi:[1,0]
	v_pk_mul_f32 v[8:9], v[8:9], v[74:75] op_sel_hi:[1,0]
	v_pk_mul_f32 v[6:7], v[6:7], v[74:75] op_sel_hi:[1,0]
	v_pk_mul_f32 v[4:5], v[4:5], v[74:75] op_sel_hi:[1,0]
	v_pk_mul_f32 v[2:3], v[2:3], v[74:75] op_sel_hi:[1,0]
	s_branch .LBB0_866
